# v2 + GEMM K-loops: per-segment s_setprio flips deleted, one static s_setprio 1 for waves 0-3 (the leading half) at each GEMM phase entry
# speedup vs baseline: 1.0123x; 1.0068x over previous
.LBB0_210:
	s_and_b32 s3, s3, 3
	s_lshl_b32 s12, s2, 13
	s_lshl_b32 s13, s3, 9
	s_add_u32 s4, s88, 0x188800
	s_addc_u32 s5, s89, 0
	s_add_i32 m0, s68, 0x18000
	v_lshl_add_u64 v[8:9], s[4:5], 0, v[132:133]
	s_waitcnt vmcnt(2)
	s_barrier
	global_load_lds_dwordx4 v[8:9], off
	v_lshl_add_u64 v[8:9], s[4:5], 0, v[136:137]
	s_add_i32 m0, s68, 0x1a000
	s_mov_b64 s[52:53], 0x80
	s_add_i32 s8, s68, 0x8000
	s_add_i32 s9, s68, 0xa000
	global_load_lds_dwordx4 v[8:9], off
	v_lshl_add_u64 v[2:3], v[2:3], 0, s[52:53]
	s_mov_b32 m0, s8
	s_add_u32 s4, s88, 0x189000
	global_load_lds_dwordx4 v[2:3], off
	v_lshl_add_u64 v[2:3], v[4:5], 0, s[52:53]
	s_mov_b32 m0, s9
	s_addc_u32 s5, s89, 0
	global_load_lds_dwordx4 v[2:3], off
	s_add_i32 m0, s68, 0x1c000
	v_lshl_add_u64 v[2:3], s[4:5], 0, v[132:133]
	global_load_lds_dwordx4 v[2:3], off
	v_lshl_add_u64 v[2:3], s[4:5], 0, v[136:137]
	s_add_i32 m0, s68, 0x1e000
	v_and_b32_e32 v1, 15, v6
	global_load_lds_dwordx4 v[2:3], off
	v_bfe_u32 v2, v6, 4, 2
	v_lshlrev_b32_e32 v3, 4, v2
	v_lshlrev_b32_e32 v4, 2, v6
	v_lshl_or_b32 v3, v1, 6, v3
	v_and_b32_e32 v4, 32, v4
	v_lshlrev_b32_e32 v2, 11, v2
	v_lshlrev_b32_e32 v1, 4, v1
	s_cmpk_lt_u32 s0, 0x100
	v_bitop3_b32 v3, v3, s12, v4 bitop3:0xde
	v_or3_b32 v1, s13, v1, v2
	s_cselect_b64 s[66:67], -1, 0
	v_bfe_u32 v2, v6, 2, 4
	v_and_b32_e32 v4, 3, v6
	s_ashr_i32 s0, s92, 31
	v_lshl_or_b32 v143, s2, 6, v2
	v_lshlrev_b32_e32 v2, 3, v4
	v_writelane_b32 v249, s0, 58
	v_lshl_or_b32 v144, s3, 5, v2
	v_readlane_b32 s2, v249, 2
	s_mov_b32 s0, s2
	s_ashr_i32 s2, s2, 31
	v_readlane_b32 s3, v249, 3
	v_writelane_b32 v249, s2, 60
	s_and_b32 s2, s0, 7
	s_waitcnt vmcnt(6)
	v_writelane_b32 v249, s2, 61
	s_bfe_u32 s2, s0, 0x30003
	v_and_b32_e32 v5, 60, v6
	v_writelane_b32 v249, s2, 62
	s_ashr_i32 s0, s0, 6
	v_lshl_or_b32 v142, v4, 6, v5
	v_writelane_b32 v249, s0, 63
	v_mov_b32_e32 v146, s1
	s_add_i32 s0, 0, 0x10000
	s_add_i32 s1, 0, 0x14000
	v_add_u32_e32 v145, 0, v3
	s_movk_i32 s72, 0x6080
	v_mov_b64_e32 v[138:139], 0x8ff
	s_barrier
	v_readfirstlane_b32 s98, v0
	s_nop 3
	s_and_b32 s98, s98, 0x3ff
	s_cmp_ge_u32 s98, 0x100
	s_cbranch_scc1 .Lprio_done0
	s_setprio 1

.LBB0_519:
	s_add_u32 s19, s50, 0x108000
	s_addc_u32 s52, s51, 0
	s_and_b32 s18, s4, 3
	s_lshl_b32 s20, s3, 13
	s_lshl_b32 s21, s18, 9
	s_add_u32 s4, s78, 0x88800
	s_addc_u32 s5, s79, 0
	s_add_i32 m0, s94, 0x18000
	v_lshl_add_u64 v[8:9], s[4:5], 0, v[140:141]
	s_waitcnt vmcnt(2)
	s_barrier
	global_load_lds_dwordx4 v[8:9], off
	v_lshl_add_u64 v[8:9], s[4:5], 0, v[144:145]
	s_add_i32 m0, s94, 0x1a000
	s_mov_b64 s[56:57], 0x80
	s_add_i32 s53, s94, 0x8000
	s_add_i32 s92, s94, 0xa000
	global_load_lds_dwordx4 v[8:9], off
	v_lshl_add_u64 v[2:3], v[2:3], 0, s[56:57]
	s_mov_b32 m0, s53
	s_add_u32 s4, s78, 0x89000
	global_load_lds_dwordx4 v[2:3], off
	v_lshl_add_u64 v[2:3], v[4:5], 0, s[56:57]
	s_mov_b32 m0, s92
	s_addc_u32 s5, s79, 0
	global_load_lds_dwordx4 v[2:3], off
	s_add_i32 m0, s94, 0x1c000
	v_lshl_add_u64 v[2:3], s[4:5], 0, v[140:141]
	global_load_lds_dwordx4 v[2:3], off
	v_lshl_add_u64 v[2:3], s[4:5], 0, v[144:145]
	s_add_i32 m0, s94, 0x1e000
	v_and_b32_e32 v1, 15, v6
	global_load_lds_dwordx4 v[2:3], off
	v_bfe_u32 v2, v6, 4, 2
	v_lshlrev_b32_e32 v3, 4, v2
	v_lshlrev_b32_e32 v4, 2, v6
	v_lshl_or_b32 v3, v1, 6, v3
	v_and_b32_e32 v4, 32, v4
	v_lshlrev_b32_e32 v2, 11, v2
	v_lshlrev_b32_e32 v1, 4, v1
	v_bitop3_b32 v18, v3, s20, v4 bitop3:0xde
	v_or3_b32 v1, s21, v1, v2
	v_and_b32_e32 v2, 3, v6
	v_and_b32_e32 v3, 60, v6
	s_cmpk_lt_u32 s14, 0x100
	v_lshl_or_b32 v184, v2, 6, v3
	v_bfe_u32 v3, v6, 2, 4
	v_lshlrev_b32_e32 v2, 3, v2
	v_readlane_b32 s4, v249, 49
	s_cselect_b64 s[58:59], -1, 0
	v_lshl_or_b32 v185, s18, 5, v2
	v_lshl_or_b32 v2, s3, 6, v3
	s_ashr_i32 s3, s4, 31
	v_readlane_b32 s5, v249, 50
	v_writelane_b32 v249, s3, 60
	s_waitcnt vmcnt(6)
	v_or_b32_e32 v4, 16, v2
	v_readlane_b32 s4, v249, 2
	s_ashr_i32 s3, s4, 31
	v_readlane_b32 s5, v249, 3
	v_writelane_b32 v249, s3, 61
	s_and_b32 s3, s4, 4
	v_writelane_b32 v249, s3, 62
	s_bfe_u32 s3, s4, 0x30003
	v_writelane_b32 v249, s3, 63
	s_lshl_b32 s3, s4, 2
	s_and_b32 s3, s3, 12
	s_ashr_i32 s4, s4, 6
	v_or_b32_e32 v6, 32, v2
	v_or_b32_e32 v8, 48, v2
	v_add_u32_e32 v10, 0x80, v2
	v_add_u32_e32 v12, 0x90, v2
	v_add_u32_e32 v14, 0xa0, v2
	v_add_u32_e32 v16, 0xb0, v2
	s_add_i32 s3, s3, s4
	v_ashrrev_i32_e32 v3, 31, v2
	v_ashrrev_i32_e32 v5, 31, v4
	v_ashrrev_i32_e32 v7, 31, v6
	v_ashrrev_i32_e32 v9, 31, v8
	v_ashrrev_i32_e32 v11, 31, v10
	v_ashrrev_i32_e32 v13, 31, v12
	v_ashrrev_i32_e32 v15, 31, v14
	v_ashrrev_i32_e32 v17, 31, v16
	v_writelane_b32 v248, s3, 3
	s_movk_i32 s3, 0x2080
	v_lshlrev_b64 v[146:147], 14, v[2:3]
	v_lshlrev_b64 v[148:149], 14, v[4:5]
	v_lshlrev_b64 v[150:151], 14, v[6:7]
	v_lshlrev_b64 v[152:153], 14, v[8:9]
	v_lshlrev_b64 v[154:155], 14, v[10:11]
	v_lshlrev_b64 v[156:157], 14, v[12:13]
	v_lshlrev_b64 v[158:159], 14, v[14:15]
	v_lshlrev_b64 v[160:161], 14, v[16:17]
	v_mad_i64_i32 v[162:163], s[4:5], v2, s3, 0
	v_mad_i64_i32 v[164:165], s[4:5], v4, s3, 0
	v_mad_i64_i32 v[166:167], s[4:5], v6, s3, 0
	v_mad_i64_i32 v[168:169], s[4:5], v8, s3, 0
	v_mad_i64_i32 v[170:171], s[4:5], v10, s3, 0
	v_mad_i64_i32 v[172:173], s[4:5], v12, s3, 0
	v_mad_i64_i32 v[174:175], s[4:5], v14, s3, 0
	v_mad_i64_i32 v[176:177], s[4:5], v16, s3, 0
	v_mov_b32_e32 v187, s2
	s_add_i32 s93, 0, 0x10000
	s_add_i32 s18, 0, 0x14000
	v_add_u32_e32 v186, 0, v18
	v_mov_b64_e32 v[178:179], 0x2ff
	s_mov_b32 s36, 0
	s_barrier
	v_readfirstlane_b32 s98, v0
	s_nop 3
	s_and_b32 s98, s98, 0x3ff
	s_cmp_ge_u32 s98, 0x100
	s_cbranch_scc1 .Lprio_done1
	s_setprio 1

.LBB0_757:
	s_and_b32 s22, s4, 3
	s_lshl_b32 s23, s3, 13
	s_lshl_b32 s24, s22, 9
	s_add_u32 s4, s56, 0x208800
	s_addc_u32 s5, s57, 0
	s_add_i32 m0, s36, 0x18000
	v_lshl_add_u64 v[8:9], s[4:5], 0, v[132:133]
	s_waitcnt vmcnt(2)
	s_barrier
	global_load_lds_dwordx4 v[8:9], off
	v_lshl_add_u64 v[8:9], s[4:5], 0, v[136:137]
	s_add_i32 m0, s36, 0x1a000
	s_mov_b64 s[14:15], 0x80
	s_add_i32 s77, s36, 0x8000
	s_add_i32 s78, s36, 0xa000
	global_load_lds_dwordx4 v[8:9], off
	v_lshl_add_u64 v[2:3], v[2:3], 0, s[14:15]
	s_mov_b32 m0, s77
	s_add_u32 s4, s56, 0x209000
	global_load_lds_dwordx4 v[2:3], off
	v_lshl_add_u64 v[2:3], v[4:5], 0, s[14:15]
	s_mov_b32 m0, s78
	s_addc_u32 s5, s57, 0
	global_load_lds_dwordx4 v[2:3], off
	s_add_i32 m0, s36, 0x1c000
	v_lshl_add_u64 v[2:3], s[4:5], 0, v[132:133]
	global_load_lds_dwordx4 v[2:3], off
	v_lshl_add_u64 v[2:3], s[4:5], 0, v[136:137]
	s_add_i32 m0, s36, 0x1e000
	v_and_b32_e32 v1, 15, v6
	global_load_lds_dwordx4 v[2:3], off
	v_bfe_u32 v2, v6, 4, 2
	v_lshlrev_b32_e32 v3, 4, v2
	v_lshl_or_b32 v3, v1, 6, v3
	v_lshlrev_b32_e32 v4, 2, v6
	v_lshlrev_b32_e32 v2, 11, v2
	v_lshlrev_b32_e32 v1, 4, v1
	v_and_b32_e32 v4, 32, v4
	v_or3_b32 v1, s24, v1, v2
	s_cmpk_lt_u32 s20, 0x100
	v_bfe_u32 v2, v6, 2, 4
	v_readlane_b32 s4, v249, 2
	v_bitop3_b32 v3, v3, s23, v4 bitop3:0xde
	s_waitcnt vmcnt(6)
	s_cselect_b64 s[30:31], -1, 0
	v_and_b32_e32 v4, 3, v6
	v_lshl_or_b32 v143, s3, 6, v2
	s_lshl_b32 s3, s4, 2
	v_and_b32_e32 v5, 60, v6
	v_lshlrev_b32_e32 v2, 3, v4
	s_and_b32 s82, s3, 28
	s_ashr_i32 s3, s4, 6
	v_lshl_or_b32 v142, v4, 6, v5
	v_lshl_or_b32 v144, s22, 5, v2
	s_ashr_i32 s79, s92, 31
	s_ashr_i32 s80, s4, 31
	s_bfe_u32 s81, s4, 0x30003
	s_add_i32 s82, s82, s3
	v_mov_b32_e32 v146, s2
	s_add_i32 s83, 0, 0x10000
	s_add_i32 s84, 0, 0x14000
	v_add_u32_e32 v145, 0, v3
	s_mov_b32 s85, 0x8080
	v_mov_b64_e32 v[138:139], 0xbff
	s_barrier
	v_readlane_b32 s5, v249, 3
	v_readfirstlane_b32 s98, v0
	s_nop 3
	s_and_b32 s98, s98, 0x3ff
	s_cmp_ge_u32 s98, 0x100
	s_cbranch_scc1 .Lprio_done2
	s_setprio 1

.LBB0_894:
	s_add_u32 s76, s50, 0x114000
	s_addc_u32 s77, s51, 0
	s_and_b32 s18, s12, 3
	s_lshl_b32 s15, s3, 13
	s_lshl_b32 s22, s18, 9
	s_add_u32 s12, s40, 0x88800
	s_addc_u32 s13, s41, 0
	s_add_i32 m0, s33, 0x18000
	v_lshl_add_u64 v[6:7], s[12:13], 0, v[138:139]
	s_waitcnt vmcnt(2)
	s_barrier
	global_load_lds_dwordx4 v[6:7], off
	v_lshl_add_u64 v[6:7], s[12:13], 0, v[142:143]
	s_add_i32 m0, s33, 0x1a000
	s_mov_b64 s[12:13], 0x80
	s_add_i32 s78, s33, 0x8000
	s_add_i32 s79, s33, 0xa000
	global_load_lds_dwordx4 v[6:7], off
	v_lshl_add_u64 v[2:3], v[2:3], 0, s[12:13]
	s_mov_b32 m0, s78
	s_add_u32 s20, s40, 0x89000
	global_load_lds_dwordx4 v[2:3], off
	v_lshl_add_u64 v[2:3], v[4:5], 0, s[12:13]
	s_mov_b32 m0, s79
	s_addc_u32 s21, s41, 0
	global_load_lds_dwordx4 v[2:3], off
	s_add_i32 m0, s33, 0x1c000
	v_lshl_add_u64 v[2:3], s[20:21], 0, v[138:139]
	global_load_lds_dwordx4 v[2:3], off
	v_lshl_add_u64 v[2:3], s[20:21], 0, v[142:143]
	s_add_i32 m0, s33, 0x1e000
	v_and_b32_e32 v1, 15, v0
	global_load_lds_dwordx4 v[2:3], off
	v_bfe_u32 v2, v0, 4, 2
	v_lshlrev_b32_e32 v3, 4, v2
	v_lshl_or_b32 v3, v1, 6, v3
	v_lshlrev_b32_e32 v4, 2, v0
	v_lshlrev_b32_e32 v2, 11, v2
	v_lshlrev_b32_e32 v1, 4, v1
	v_and_b32_e32 v4, 32, v4
	v_or3_b32 v182, s22, v1, v2
	s_cmpk_lt_u32 s14, 0x100
	v_and_b32_e32 v1, 3, v0
	v_and_b32_e32 v2, 60, v0
	v_bfe_u32 v0, v0, 2, 4
	v_readlane_b32 s20, v249, 2
	v_bitop3_b32 v16, v3, s15, v4 bitop3:0xde
	s_cselect_b64 s[14:15], -1, 0
	v_lshl_or_b32 v0, s3, 6, v0
	s_lshl_b32 s3, s20, 2
	s_waitcnt vmcnt(6)
	v_lshlrev_b32_e32 v3, 3, v1
	v_lshl_or_b32 v184, v1, 6, v2
	v_or_b32_e32 v2, 16, v0
	v_or_b32_e32 v4, 32, v0
	v_or_b32_e32 v6, 48, v0
	v_add_u32_e32 v8, 0x80, v0
	v_add_u32_e32 v10, 0x90, v0
	v_add_u32_e32 v12, 0xa0, v0
	v_add_u32_e32 v14, 0xb0, v0
	s_and_b32 s84, s3, 12
	s_ashr_i32 s3, s20, 6
	v_lshl_or_b32 v183, s18, 5, v3
	v_ashrrev_i32_e32 v1, 31, v0
	v_ashrrev_i32_e32 v3, 31, v2
	v_ashrrev_i32_e32 v5, 31, v4
	v_ashrrev_i32_e32 v7, 31, v6
	v_ashrrev_i32_e32 v9, 31, v8
	v_ashrrev_i32_e32 v11, 31, v10
	v_ashrrev_i32_e32 v13, 31, v12
	v_ashrrev_i32_e32 v15, 31, v14
	v_readlane_b32 s21, v249, 3
	s_add_i32 s84, s84, s3
	s_movk_i32 s3, 0x2080
	v_lshlrev_b64 v[144:145], 14, v[0:1]
	v_lshlrev_b64 v[146:147], 14, v[2:3]
	v_lshlrev_b64 v[148:149], 14, v[4:5]
	v_lshlrev_b64 v[150:151], 14, v[6:7]
	v_lshlrev_b64 v[152:153], 14, v[8:9]
	v_lshlrev_b64 v[154:155], 14, v[10:11]
	v_lshlrev_b64 v[156:157], 14, v[12:13]
	v_lshlrev_b64 v[158:159], 14, v[14:15]
	s_ashr_i32 s80, s92, 31
	s_ashr_i32 s81, s20, 31
	s_and_b32 s82, s20, 4
	s_bfe_u32 s83, s20, 0x30003
	v_mad_i64_i32 v[160:161], s[20:21], v0, s3, 0
	v_mad_i64_i32 v[162:163], s[20:21], v2, s3, 0
	v_mad_i64_i32 v[164:165], s[20:21], v4, s3, 0
	v_mad_i64_i32 v[166:167], s[20:21], v6, s3, 0
	v_mad_i64_i32 v[168:169], s[20:21], v8, s3, 0
	v_mad_i64_i32 v[170:171], s[20:21], v10, s3, 0
	v_mad_i64_i32 v[172:173], s[20:21], v12, s3, 0
	v_mad_i64_i32 v[174:175], s[20:21], v14, s3, 0
	v_mov_b32_e32 v186, s2
	s_movk_i32 s18, 0x61
	s_add_i32 s36, 0, 0x10000
	s_add_i32 s37, 0, 0x14000
	v_add_u32_e32 v185, 0, v16
	v_mov_b64_e32 v[176:177], 0x2ff
	s_barrier
	v_readfirstlane_b32 s98, v0
	s_nop 3
	s_and_b32 s98, s98, 0x3ff
	s_cmp_ge_u32 s98, 0x100
	s_cbranch_scc1 .Lprio_done3
	s_setprio 1
